# first and final RMSNorm loops: wave sum by DPP adds and permlane swaps (no LDS round trips)
# speedup vs baseline: 1.0036x; 1.0000x over previous
.LBB0_124:
	global_load_dwordx4 v[30:33], v[22:23], off offset:-3072
	global_load_dwordx4 v[34:37], v[22:23], off offset:-2048
	global_load_dwordx4 v[38:41], v[22:23], off offset:-1024
	global_load_dwordx4 v[42:45], v[22:23], off
	v_add_u32_e32 v18, s16, v18
	v_cmp_lt_i32_e32 vcc, s12, v18
	s_or_b64 s[10:11], vcc, s[10:11]
	v_lshl_add_u64 v[22:23], v[22:23], 0, s[8:9]
	s_waitcnt vmcnt(3)
	v_mov_b32_e32 v48, v31
	s_waitcnt vmcnt(2)
	v_mov_b32_e32 v49, v35
	v_mov_b32_e32 v46, v30
	v_mov_b32_e32 v47, v34
	s_waitcnt vmcnt(1)
	v_mov_b32_e32 v56, v39
	s_waitcnt vmcnt(0)
	v_mov_b32_e32 v57, v43
	v_pk_mul_f32 v[48:49], v[48:49], v[48:49]
	v_mov_b32_e32 v50, v32
	v_mov_b32_e32 v51, v36
	v_mov_b32_e32 v54, v38
	v_mov_b32_e32 v55, v42
	v_pk_mul_f32 v[56:57], v[56:57], v[56:57]
	v_pk_fma_f32 v[46:47], v[46:47], v[46:47], v[48:49]
	v_mov_b32_e32 v52, v33
	v_mov_b32_e32 v53, v37
	v_mov_b32_e32 v58, v40
	v_mov_b32_e32 v59, v44
	v_pk_fma_f32 v[48:49], v[54:55], v[54:55], v[56:57]
	v_pk_fma_f32 v[46:47], v[50:51], v[50:51], v[46:47]
	v_mov_b32_e32 v60, v41
	v_mov_b32_e32 v61, v45
	v_pk_fma_f32 v[48:49], v[58:59], v[58:59], v[48:49]
	v_pk_fma_f32 v[46:47], v[52:53], v[52:53], v[46:47]
	v_pk_fma_f32 v[48:49], v[60:61], v[60:61], v[48:49]
	v_add_f32_e32 v46, v46, v47
	v_add_f32_e32 v46, v46, v48
	v_add_f32_e32 v46, v46, v49
	s_nop 1
	v_add_f32_dpp v46, v46, v46 quad_perm:[1,0,3,2] row_mask:0xf bank_mask:0xf
	s_nop 1
	v_add_f32_dpp v46, v46, v46 quad_perm:[2,3,0,1] row_mask:0xf bank_mask:0xf
	s_nop 1
	v_add_f32_dpp v46, v46, v46 row_half_mirror row_mask:0xf bank_mask:0xf
	s_nop 1
	v_add_f32_dpp v46, v46, v46 row_mirror row_mask:0xf bank_mask:0xf
	v_mov_b32_e32 v47, v46
	s_nop 1
	v_permlane16_swap_b32_e32 v46, v47
	v_add_f32_e32 v46, v46, v47
	v_mov_b32_e32 v47, v46
	s_nop 1
	v_permlane32_swap_b32_e32 v46, v47
	v_add_f32_e32 v46, v46, v47
	v_fmamk_f32 v46, v46, 0x3a800000, v19
	v_mul_f32_e32 v47, 0x4b800000, v46
	v_cmp_gt_f32_e32 vcc, s3, v46
	s_nop 1
	v_cndmask_b32_e32 v46, v46, v47, vcc
	v_rsq_f32_e32 v46, v46
	s_nop 0
	v_mul_f32_e32 v47, 0x45800000, v46
	v_cndmask_b32_e32 v46, v46, v47, vcc
	v_pk_mul_f32 v[30:31], v[30:31], v[46:47] op_sel_hi:[1,0]
	v_pk_mul_f32 v[32:33], v[32:33], v[46:47] op_sel_hi:[1,0]
	v_pk_mul_f32 v[34:35], v[34:35], v[46:47] op_sel_hi:[1,0]
	v_pk_mul_f32 v[36:37], v[36:37], v[46:47] op_sel_hi:[1,0]
	v_pk_mul_f32 v[38:39], v[38:39], v[46:47] op_sel_hi:[1,0]
	v_pk_mul_f32 v[40:41], v[40:41], v[46:47] op_sel_hi:[1,0]
	v_pk_mul_f32 v[42:43], v[42:43], v[46:47] op_sel_hi:[1,0]
	v_pk_mul_f32 v[44:45], v[44:45], v[46:47] op_sel_hi:[1,0]
	v_pk_mul_f32 v[32:33], v[4:5], v[32:33]
	v_pk_mul_f32 v[30:31], v[2:3], v[30:31]
	v_pk_mul_f32 v[36:37], v[8:9], v[36:37]
	v_pk_mul_f32 v[34:35], v[6:7], v[34:35]
	v_pk_mul_f32 v[40:41], v[12:13], v[40:41]
	v_pk_mul_f32 v[38:39], v[10:11], v[38:39]
	v_pk_mul_f32 v[44:45], v[16:17], v[44:45]
	v_pk_mul_f32 v[42:43], v[14:15], v[42:43]
	v_cvt_pk_bf16_f32 v30, v30, v31
	v_cvt_pk_bf16_f32 v31, v32, v33
	v_cvt_pk_bf16_f32 v32, v34, v35
	v_cvt_pk_bf16_f32 v33, v36, v37
	v_cvt_pk_bf16_f32 v34, v38, v39
	v_cvt_pk_bf16_f32 v35, v40, v41
	v_cvt_pk_bf16_f32 v36, v42, v43
	v_cvt_pk_bf16_f32 v37, v44, v45
	global_store_dwordx2 v[20:21], v[30:31], off
	global_store_dwordx2 v[20:21], v[32:33], off offset:512
	global_store_dwordx2 v[20:21], v[34:35], off offset:1024
	global_store_dwordx2 v[20:21], v[36:37], off offset:1536
	v_lshl_add_u64 v[20:21], v[20:21], 0, s[6:7]
	s_andn2_b64 exec, exec, s[10:11]
	s_cbranch_execnz .LBB0_124

.LBB0_1443:
	global_load_dwordx4 v[30:33], v[20:21], off offset:-1024
	global_load_dwordx4 v[204:207], v[20:21], off
	v_add_u32_e32 v18, s2, v18
	s_waitcnt vmcnt(1)
	v_lshlrev_b32_e32 v34, 16, v30
	v_and_b32_e32 v35, 0xffff0000, v30
	v_lshlrev_b32_e32 v36, 16, v31
	v_and_b32_e32 v37, 0xffff0000, v31
	v_lshlrev_b32_e32 v38, 16, v32
	v_and_b32_e32 v39, 0xffff0000, v32
	v_lshlrev_b32_e32 v40, 16, v33
	v_and_b32_e32 v41, 0xffff0000, v33
	v_mul_f32_e32 v0, v35, v35
	v_fmac_f32_e32 v0, v34, v34
	v_fmac_f32_e32 v0, v36, v36
	v_fmac_f32_e32 v0, v37, v37
	v_fmac_f32_e32 v0, v38, v38
	v_fmac_f32_e32 v0, v39, v39
	v_fmac_f32_e32 v0, v40, v40
	v_fmac_f32_e32 v0, v41, v41
	v_lshl_add_u64 v[20:21], v[20:21], 0, s[46:47]
	s_waitcnt vmcnt(0)
	v_lshlrev_b32_e32 v42, 16, v204
	v_and_b32_e32 v43, 0xffff0000, v204
	v_fmac_f32_e32 v0, v42, v42
	v_lshlrev_b32_e32 v44, 16, v205
	v_fmac_f32_e32 v0, v43, v43
	v_and_b32_e32 v46, 0xffff0000, v206
	v_and_b32_e32 v45, 0xffff0000, v205
	v_fmac_f32_e32 v0, v44, v44
	v_lshlrev_b32_e32 v49, 16, v206
	v_mov_b32_e32 v48, v46
	v_fmac_f32_e32 v0, v45, v45
	v_pk_mul_f32 v[30:31], v[48:49], v[48:49]
	v_lshlrev_b32_e32 v51, 16, v207
	v_add_f32_e32 v0, v31, v0
	v_add_f32_e32 v19, v30, v0
	v_and_b32_e32 v0, 0xffff0000, v207
	v_mov_b32_e32 v50, v0
	v_pk_mul_f32 v[30:31], v[50:51], v[50:51]
	v_and_b32_e32 v47, s0, v207
	v_add_f32_e32 v19, v31, v19
	v_add_f32_e32 v19, v30, v19
	s_nop 1
	v_add_f32_dpp v19, v19, v19 quad_perm:[1,0,3,2] row_mask:0xf bank_mask:0xf
	s_nop 1
	v_add_f32_dpp v19, v19, v19 quad_perm:[2,3,0,1] row_mask:0xf bank_mask:0xf
	s_nop 1
	v_add_f32_dpp v19, v19, v19 row_half_mirror row_mask:0xf bank_mask:0xf
	s_nop 1
	v_add_f32_dpp v19, v19, v19 row_mirror row_mask:0xf bank_mask:0xf
	v_mov_b32_e32 v30, v19
	s_nop 1
	v_permlane16_swap_b32_e32 v19, v30
	v_add_f32_e32 v19, v19, v30
	v_mov_b32_e32 v30, v19
	s_nop 1
	v_permlane32_swap_b32_e32 v19, v30
	v_add_f32_e32 v19, v19, v30
	v_fmamk_f32 v19, v19, 0x3a800000, v194
	v_cmp_gt_f32_e32 vcc, s76, v19
	v_mul_f32_e32 v30, 0x4b800000, v19
	s_nop 0
	v_cndmask_b32_e32 v19, v19, v30, vcc
	v_rsq_f32_e32 v19, v19
	s_nop 0
	v_mul_f32_e32 v30, 0x45800000, v19
	v_cndmask_b32_e32 v52, v19, v30, vcc
	v_pk_mul_f32 v[30:31], v[34:35], v[52:53] op_sel_hi:[1,0]
	v_pk_mul_f32 v[32:33], v[36:37], v[52:53] op_sel_hi:[1,0]
	v_pk_mul_f32 v[34:35], v[38:39], v[52:53] op_sel_hi:[1,0]
	v_pk_mul_f32 v[36:37], v[40:41], v[52:53] op_sel_hi:[1,0]
	v_pk_mul_f32 v[32:33], v[8:9], v[32:33]
	v_pk_mul_f32 v[30:31], v[6:7], v[30:31]
	v_pk_mul_f32 v[36:37], v[4:5], v[36:37]
	v_pk_mul_f32 v[34:35], v[2:3], v[34:35]
	global_store_dwordx4 v[22:23], v[30:33], off
	global_store_dwordx4 v[22:23], v[34:37], off offset:16
	v_cmp_lt_i32_e32 vcc, s8, v18
	v_pk_mul_f32 v[30:31], v[42:43], v[52:53] op_sel_hi:[1,0]
	v_pk_mul_f32 v[32:33], v[44:45], v[52:53] op_sel_hi:[1,0]
	v_pk_mov_b32 v[34:35], v[48:49], v[46:47] op_sel:[1,0]
	v_pk_mov_b32 v[36:37], v[50:51], v[0:1] op_sel:[1,0]
	v_pk_mul_f32 v[32:33], v[16:17], v[32:33]
	v_pk_mul_f32 v[30:31], v[14:15], v[30:31]
	v_pk_mul_f32 v[34:35], v[52:53], v[34:35] op_sel_hi:[0,1]
	v_pk_mul_f32 v[36:37], v[52:53], v[36:37] op_sel_hi:[0,1]
	v_pk_mul_f32 v[36:37], v[12:13], v[36:37]
	v_pk_mul_f32 v[34:35], v[10:11], v[34:35]
	global_store_dwordx4 v[22:23], v[30:33], off offset:2048
	global_store_dwordx4 v[22:23], v[34:37], off offset:2064
	v_lshl_add_u64 v[22:23], v[22:23], 0, s[12:13]
	s_or_b64 s[6:7], vcc, s[6:7]
	s_andn2_b64 exec, exec, s[6:7]
	s_cbranch_execnz .LBB0_1443
